# code placement: mlp-in K-loop head padded from 4 to 0 mod 8 bytes (all four GEMM loop heads now 8-byte aligned)
# baseline (speedup 1.0000x reference)
; #define PG8_STAGE(bufoff, gbase, goff, voff) do { _Pragma("unroll") for (int _i = 0; _i < 2; ++_i) \
;     __builtin_amdgcn_global_load_lds((const unsigned*)((gbase) + (size_t)(goff) + (voff)[_i]), (LAS unsigned*)(lds + (bufoff) + ldsw + _i * 8192), 16, 0, 0); } while (0)
; #define PG8_LDA(dst, b, h) do { _Pragma("unroll") for (int m = 0; m < 4; ++m) _Pragma("unroll") for (int k = 0; k < 2; ++k) dst[m][k] = *(const LAS bf16x8*)(lds + PG8_SA(b, h) + aoff + m * 2048 + k * 1024); } while (0)
; #define PG8_LDB(dst, b, h) do { _Pragma("unroll") for (int n = 0; n < 2; ++n) _Pragma("unroll") for (int k = 0; k < 2; ++k) dst[n][k] = *(const LAS bf16x8*)(lds + PG8_SB(b, h) + boff + n * 2048 + k * 1024); } while (0)
; #define PG8_MMA(ai, bj, At, Bt) do { __builtin_amdgcn_s_setprio(1); _Pragma("unroll") for (int m = 0; m < 4; ++m) _Pragma("unroll") for (int n = 0; n < 2; ++n) _Pragma("unroll") for (int k = 0; k < 2; ++k) \
;     acc[ai][bj][m][n] = __builtin_amdgcn_mfma_f32_16x16x32_bf16(Bt[n][k], At[m][k], acc[ai][bj][m][n], 0, 0, 0); __builtin_amdgcn_s_setprio(0); } while (0)
; #define PG8_WAIT_L(n) asm volatile("s_waitcnt lgkmcnt(" #n ")" ::: "memory")
; #define PG8_BAR __builtin_amdgcn_s_barrier()
; template <class Epi>
; DI void gemm_phase(LAS unsigned char* lds, const GemmD g, const Order& S, const Epi& E) {
;     ...
;     const bool has_next = S.next(ui + 1, nxt);
;     const unsigned nA = has_next ? (unsigned)nxt.pm * 2u * hstepA + (unsigned)nxt.kg * ustep : cA;
;     const unsigned nB = has_next ? (unsigned)nxt.pn * 2u * hstepB + (unsigned)nxt.kg * ustep : cB;
;     for (int t = 0; t < nt; t += 2) {
;       const bool last = (t == nt - 2);
;       const unsigned a1 = cA + (unsigned)(t + 1) * kstep;
;       const unsigned a2 = last ? nA : cA + (unsigned)(t + 2) * kstep; const unsigned b2 = last ? nB : cB + (unsigned)(t + 2) * kstep;
;       const unsigned a3 = a2 + kstep; const unsigned b3 = b2 + kstep;
;       PG8_LDB(B0, 0, 0); PG8_SCHED; PG8_LDA(At, 0, 0); PG8_STAGE(PG8_SA(1, 1), gA, a1 + hstepA, voffA);
;       PG8_WAIT_L(8); PG8_BAR; PG8_WAIT_L(0); PG8_MMA(0, 0, At, B0); PG8_BAR; PG8_SCHED;
;     ...
; #pragma unroll
;       for (int a = 0; a < 2; ++a)
; #pragma unroll
;         for (int b = 0; b < 2; ++b)
; #pragma unroll
;           for (int m = 0; m < 4; ++m)
; #pragma unroll
;             for (int n = 0; n < 2; ++n) acc[a][b][m][n] = (f32x4){0.f, 0.f, 0.f, 0.f};
.LBB0_234:
	v_mov_b64_e32 v[0:1], 0x800
	v_cmp_lt_i64_e32 vcc, s[6:7], v[0:1]
	s_lshl_b32 s31, s11, 19
	s_and_b64 s[6:7], vcc, exec
	s_cselect_b32 s66, s31, s48
	s_lshl_b32 s38, s10, 19
	s_and_b64 s[6:7], vcc, exec
	v_mov_b32_e32 v0, 0
	s_cselect_b32 s67, s38, s68
	v_lshl_add_u64 v[140:141], v[136:137], 0, s[48:49]
	v_lshl_add_u64 v[142:143], v[138:139], 0, s[48:49]
	s_add_u32 s68, s68, 0x100
	s_mov_b32 s69, -2
	s_mov_b64 s[6:7], 0
	v_mov_b32_e32 v1, v0
	v_mov_b32_e32 v2, v0
	v_mov_b32_e32 v3, v0
	v_mov_b32_e32 v4, v0
	v_mov_b32_e32 v5, v0
	v_mov_b32_e32 v6, v0
	v_mov_b32_e32 v7, v0
	v_mov_b32_e32 v16, v0
	v_mov_b32_e32 v17, v0
	v_mov_b32_e32 v18, v0
	v_mov_b32_e32 v19, v0
	v_mov_b32_e32 v20, v0
	v_mov_b32_e32 v21, v0
	v_mov_b32_e32 v22, v0
	v_mov_b32_e32 v23, v0
	v_mov_b32_e32 v34, v0
	v_mov_b32_e32 v35, v0
	v_mov_b32_e32 v36, v0
	v_mov_b32_e32 v37, v0
	v_mov_b32_e32 v38, v0
	v_mov_b32_e32 v39, v0
	v_mov_b32_e32 v40, v0
	v_mov_b32_e32 v41, v0
	v_mov_b32_e32 v50, v0
	v_mov_b32_e32 v51, v0
	v_mov_b32_e32 v52, v0
	v_mov_b32_e32 v53, v0
	v_mov_b32_e32 v54, v0
	v_mov_b32_e32 v55, v0
	v_mov_b32_e32 v56, v0
	v_mov_b32_e32 v57, v0
	v_mov_b32_e32 v8, v0
	v_mov_b32_e32 v9, v0
	v_mov_b32_e32 v10, v0
	v_mov_b32_e32 v11, v0
	v_mov_b32_e32 v12, v0
	v_mov_b32_e32 v13, v0
	v_mov_b32_e32 v14, v0
	v_mov_b32_e32 v15, v0
	v_mov_b32_e32 v24, v0
	v_mov_b32_e32 v25, v0
	v_mov_b32_e32 v26, v0
	v_mov_b32_e32 v27, v0
	v_mov_b32_e32 v28, v0
	v_mov_b32_e32 v29, v0
	v_mov_b32_e32 v30, v0
	v_mov_b32_e32 v31, v0
	v_mov_b32_e32 v42, v0
	v_mov_b32_e32 v43, v0
	v_mov_b32_e32 v44, v0
	v_mov_b32_e32 v45, v0
	v_mov_b32_e32 v46, v0
	v_mov_b32_e32 v47, v0
	v_mov_b32_e32 v48, v0
	v_mov_b32_e32 v49, v0
	v_mov_b32_e32 v58, v0
	v_mov_b32_e32 v59, v0
	v_mov_b32_e32 v60, v0
	v_mov_b32_e32 v61, v0
	v_mov_b32_e32 v62, v0
	v_mov_b32_e32 v63, v0
	v_mov_b32_e32 v64, v0
	v_mov_b32_e32 v65, v0
	v_mov_b32_e32 v66, v0
	v_mov_b32_e32 v67, v0
	v_mov_b32_e32 v68, v0
	v_mov_b32_e32 v69, v0
	v_mov_b32_e32 v70, v0
	v_mov_b32_e32 v71, v0
	v_mov_b32_e32 v72, v0
	v_mov_b32_e32 v73, v0
	s_waitcnt vmcnt(0)
	v_mov_b32_e32 v82, v0
	v_mov_b32_e32 v83, v0
	v_mov_b32_e32 v84, v0
	v_mov_b32_e32 v85, v0
	v_mov_b32_e32 v86, v0
	v_mov_b32_e32 v87, v0
	v_mov_b32_e32 v88, v0
	v_mov_b32_e32 v89, v0
	v_mov_b32_e32 v98, v0
	v_mov_b32_e32 v99, v0
	v_mov_b32_e32 v100, v0
	v_mov_b32_e32 v101, v0
	v_mov_b32_e32 v102, v0
	v_mov_b32_e32 v103, v0
	v_mov_b32_e32 v104, v0
	v_mov_b32_e32 v105, v0
	v_mov_b32_e32 v114, v0
	v_mov_b32_e32 v115, v0
	v_mov_b32_e32 v116, v0
	v_mov_b32_e32 v117, v0
	v_mov_b32_e32 v118, v0
	v_mov_b32_e32 v119, v0
	v_mov_b32_e32 v120, v0
	v_mov_b32_e32 v121, v0
	v_mov_b32_e32 v74, v0
	v_mov_b32_e32 v75, v0
	v_mov_b32_e32 v76, v0
	v_mov_b32_e32 v77, v0
	v_mov_b32_e32 v78, v0
	v_mov_b32_e32 v79, v0
	v_mov_b32_e32 v80, v0
	v_mov_b32_e32 v81, v0
	v_mov_b32_e32 v90, v0
	v_mov_b32_e32 v91, v0
	v_mov_b32_e32 v92, v0
	v_mov_b32_e32 v93, v0
	v_mov_b32_e32 v94, v0
	v_mov_b32_e32 v95, v0
	v_mov_b32_e32 v96, v0
	v_mov_b32_e32 v97, v0
	v_mov_b32_e32 v106, v0
	v_mov_b32_e32 v107, v0
	v_mov_b32_e32 v108, v0
	v_mov_b32_e32 v109, v0
	v_mov_b32_e32 v110, v0
	v_mov_b32_e32 v111, v0
	v_mov_b32_e32 v112, v0
	v_mov_b32_e32 v113, v0
	v_mov_b32_e32 v122, v0
	v_mov_b32_e32 v123, v0
	v_mov_b32_e32 v124, v0
	v_mov_b32_e32 v125, v0
	v_mov_b32_e32 v126, v0
	v_mov_b32_e32 v127, v0
	v_mov_b32_e32 v128, v0
	v_mov_b32_e32 v129, v0
	s_nop 0
.LBB0_235:
	s_add_i32 s71, 0, 0x10000
	v_add_u32_e32 v148, s71, v150
	ds_read_b128 v[144:147], v148
	ds_read_b128 v[158:161], v148 offset:1024
	ds_read_b128 v[162:165], v148 offset:2048
	ds_read_b128 v[168:171], v148 offset:3072
	s_add_i32 s8, s48, s6
	s_addk_i32 s8, 0x100
	s_add_i32 s9, s68, s6
	s_cmpk_eq_i32 s6, 0x700
	s_cselect_b32 s72, s66, s8
	s_cselect_b32 s70, s67, s9
	v_lshl_add_u64 v[148:149], v[142:143], 0, s[6:7]
	s_add_i32 m0, s24, 0xc000
	ds_read_b128 v[172:175], v151
	ds_read_b128 v[176:179], v151 offset:1024
	ds_read_b128 v[180:183], v151 offset:2048
	ds_read_b128 v[184:187], v151 offset:3072
	ds_read_b128 v[188:191], v151 offset:4096
	ds_read_b128 v[192:195], v151 offset:5120
	ds_read_b128 v[196:199], v151 offset:6144
	ds_read_b128 v[216:219], v151 offset:7168
	global_load_lds_dwordx4 v[148:149], off
	v_lshl_add_u64 v[148:149], v[140:141], 0, s[6:7]
	s_add_i32 m0, s24, 0xe000
	s_nop 0
	global_load_lds_dwordx4 v[148:149], off
	s_waitcnt lgkmcnt(8)
	s_barrier
	s_waitcnt lgkmcnt(0)
	s_setprio 1
	s_waitcnt lgkmcnt(0)
	v_mfma_f32_16x16x32_bf16 v[126:129], v[144:147], v[172:175], v[126:129]
	v_mfma_f32_16x16x32_bf16 v[122:125], v[162:165], v[172:175], v[122:125]
	v_mfma_f32_16x16x32_bf16 v[110:113], v[144:147], v[180:183], v[110:113]
	v_mfma_f32_16x16x32_bf16 v[106:109], v[162:165], v[180:183], v[106:109]
	v_mfma_f32_16x16x32_bf16 v[94:97], v[144:147], v[188:191], v[94:97]
	v_mfma_f32_16x16x32_bf16 v[90:93], v[162:165], v[188:191], v[90:93]
	v_mfma_f32_16x16x32_bf16 v[78:81], v[144:147], v[196:199], v[78:81]
	v_mfma_f32_16x16x32_bf16 v[74:77], v[162:165], v[196:199], v[74:77]
	v_mfma_f32_16x16x32_bf16 v[126:129], v[158:161], v[176:179], v[126:129]
	v_mfma_f32_16x16x32_bf16 v[122:125], v[168:171], v[176:179], v[122:125]
	v_mfma_f32_16x16x32_bf16 v[110:113], v[158:161], v[184:187], v[110:113]
	v_mfma_f32_16x16x32_bf16 v[106:109], v[168:171], v[184:187], v[106:109]
	v_mfma_f32_16x16x32_bf16 v[94:97], v[158:161], v[192:195], v[94:97]
	v_mfma_f32_16x16x32_bf16 v[90:93], v[168:171], v[192:195], v[90:93]
	v_mfma_f32_16x16x32_bf16 v[78:81], v[158:161], v[216:219], v[78:81]
	v_mfma_f32_16x16x32_bf16 v[74:77], v[168:171], v[216:219], v[74:77]
	s_setprio 0
	s_barrier
; #define PG8_STAGE(bufoff, gbase, goff, voff) do { _Pragma("unroll") for (int _i = 0; _i < 2; ++_i) \
;     __builtin_amdgcn_global_load_lds((const unsigned*)((gbase) + (size_t)(goff) + (voff)[_i]), (LAS unsigned*)(lds + (bufoff) + ldsw + _i * 8192), 16, 0, 0); } while (0)
; #define PG8_LDA(dst, b, h) do { _Pragma("unroll") for (int m = 0; m < 4; ++m) _Pragma("unroll") for (int k = 0; k < 2; ++k) dst[m][k] = *(const LAS bf16x8*)(lds + PG8_SA(b, h) + aoff + m * 2048 + k * 1024); } while (0)
; #define PG8_LDB(dst, b, h) do { _Pragma("unroll") for (int n = 0; n < 2; ++n) _Pragma("unroll") for (int k = 0; k < 2; ++k) dst[n][k] = *(const LAS bf16x8*)(lds + PG8_SB(b, h) + boff + n * 2048 + k * 1024); } while (0)
; #define PG8_MMA(ai, bj, At, Bt) do { __builtin_amdgcn_s_setprio(1); _Pragma("unroll") for (int m = 0; m < 4; ++m) _Pragma("unroll") for (int n = 0; n < 2; ++n) _Pragma("unroll") for (int k = 0; k < 2; ++k) \
;     acc[ai][bj][m][n] = __builtin_amdgcn_mfma_f32_16x16x32_bf16(Bt[n][k], At[m][k], acc[ai][bj][m][n], 0, 0, 0); __builtin_amdgcn_s_setprio(0); } while (0)
; #define PG8_WAIT_V(n) asm volatile("s_waitcnt vmcnt(" #n ")" ::: "memory")
; #define PG8_WAIT_L(n) asm volatile("s_waitcnt lgkmcnt(" #n ")" ::: "memory")
; #define PG8_BAR __builtin_amdgcn_s_barrier()
; #define PG8_SCHED __builtin_amdgcn_sched_barrier(0)
; template <class Epi>
; DI void gemm_phase(LAS unsigned char* lds, const GemmD g, const Order& S, const Epi& E) {
;     ...
;       PG8_LDB(B1, 0, 1); PG8_STAGE(PG8_SB(0, 0), gB, b2, voffB);
;       PG8_BAR; PG8_WAIT_L(0); PG8_MMA(0, 1, At, B1); PG8_BAR;
;       PG8_LDA(At, 0, 1); PG8_STAGE(PG8_SA(0, 0), gA, a2, voffA);
;       PG8_BAR; PG8_WAIT_L(0); PG8_MMA(1, 0, At, B0); PG8_BAR; PG8_SCHED;
;       PG8_STAGE(PG8_SB(0, 1), gB, b2 + hstepB, voffB);
;       PG8_WAIT_V(6); PG8_BAR; PG8_MMA(1, 1, At, B1); PG8_BAR;
;       PG8_LDB(B0, 1, 0); PG8_SCHED; PG8_LDA(At, 1, 0); PG8_STAGE(PG8_SA(0, 1), gA, a2 + hstepA, voffA);
;       PG8_WAIT_L(8); PG8_BAR; PG8_WAIT_L(0); PG8_MMA(0, 0, At, B0); PG8_BAR; PG8_SCHED;
	s_add_i32 s73, 0, 0x14000
	s_add_u32 s8, s21, s70
	v_add_u32_e32 v148, s73, v150
	s_addc_u32 s9, s22, 0
	s_add_i32 s71, s71, s23
	ds_read_b128 v[220:223], v148
	ds_read_b128 v[224:227], v148 offset:1024
	ds_read_b128 v[228:231], v148 offset:2048
	ds_read_b128 v[232:235], v148 offset:3072
	v_lshl_add_u64 v[148:149], s[8:9], 0, v[32:33]
	s_mov_b32 m0, s71
	v_lshl_add_u64 v[152:153], s[8:9], 0, v[130:131]
	global_load_lds_dwordx4 v[148:149], off
	s_add_i32 m0, s71, 0x2000
	s_nop 0
	global_load_lds_dwordx4 v[152:153], off
	s_barrier
	s_waitcnt lgkmcnt(0)
	s_setprio 1
	s_waitcnt lgkmcnt(0)
	v_mfma_f32_16x16x32_bf16 v[118:121], v[220:223], v[172:175], v[118:121]
	v_mfma_f32_16x16x32_bf16 v[114:117], v[228:231], v[172:175], v[114:117]
	v_mfma_f32_16x16x32_bf16 v[102:105], v[220:223], v[180:183], v[102:105]
	v_mfma_f32_16x16x32_bf16 v[98:101], v[228:231], v[180:183], v[98:101]
	v_mfma_f32_16x16x32_bf16 v[86:89], v[220:223], v[188:191], v[86:89]
	v_mfma_f32_16x16x32_bf16 v[82:85], v[228:231], v[188:191], v[82:85]
	v_mfma_f32_16x16x32_bf16 v[70:73], v[220:223], v[196:199], v[70:73]
	v_mfma_f32_16x16x32_bf16 v[66:69], v[228:231], v[196:199], v[66:69]
	v_mfma_f32_16x16x32_bf16 v[118:121], v[224:227], v[176:179], v[118:121]
	v_mfma_f32_16x16x32_bf16 v[114:117], v[232:235], v[176:179], v[114:117]
	v_mfma_f32_16x16x32_bf16 v[102:105], v[224:227], v[184:187], v[102:105]
	v_mfma_f32_16x16x32_bf16 v[98:101], v[232:235], v[184:187], v[98:101]
	v_mfma_f32_16x16x32_bf16 v[86:89], v[224:227], v[192:195], v[86:89]
	v_mfma_f32_16x16x32_bf16 v[82:85], v[232:235], v[192:195], v[82:85]
	v_mfma_f32_16x16x32_bf16 v[70:73], v[224:227], v[216:219], v[70:73]
	v_mfma_f32_16x16x32_bf16 v[66:69], v[232:235], v[216:219], v[66:69]
	s_setprio 0
	s_add_u32 s8, s14, s72
	s_addc_u32 s9, s15, 0
	s_mov_b32 m0, s24
	v_lshl_add_u64 v[200:201], s[8:9], 0, v[134:135]
	s_barrier
	ds_read_b128 v[172:175], v151 offset:16384
	ds_read_b128 v[176:179], v151 offset:17408
	ds_read_b128 v[180:183], v151 offset:18432
	ds_read_b128 v[184:187], v151 offset:19456
	ds_read_b128 v[188:191], v151 offset:20480
	ds_read_b128 v[192:195], v151 offset:21504
	ds_read_b128 v[196:199], v151 offset:22528
	ds_read_b128 v[216:219], v151 offset:23552
	global_load_lds_dwordx4 v[200:201], off
	v_lshl_add_u64 v[204:205], s[8:9], 0, v[132:133]
	s_mov_b32 m0, s25
	s_nop 0
	global_load_lds_dwordx4 v[204:205], off
	s_barrier
	s_waitcnt lgkmcnt(0)
	s_setprio 1
	s_waitcnt lgkmcnt(0)
	v_mfma_f32_16x16x32_bf16 v[62:65], v[144:147], v[172:175], v[62:65]
	v_mfma_f32_16x16x32_bf16 v[58:61], v[162:165], v[172:175], v[58:61]
	v_mfma_f32_16x16x32_bf16 v[46:49], v[144:147], v[180:183], v[46:49]
	v_mfma_f32_16x16x32_bf16 v[42:45], v[162:165], v[180:183], v[42:45]
	v_mfma_f32_16x16x32_bf16 v[28:31], v[144:147], v[188:191], v[28:31]
	v_mfma_f32_16x16x32_bf16 v[24:27], v[162:165], v[188:191], v[24:27]
	v_mfma_f32_16x16x32_bf16 v[12:15], v[144:147], v[196:199], v[12:15]
	v_mfma_f32_16x16x32_bf16 v[8:11], v[162:165], v[196:199], v[8:11]
	v_mfma_f32_16x16x32_bf16 v[62:65], v[158:161], v[176:179], v[62:65]
	v_mfma_f32_16x16x32_bf16 v[58:61], v[168:171], v[176:179], v[58:61]
	v_mfma_f32_16x16x32_bf16 v[46:49], v[158:161], v[184:187], v[46:49]
	v_mfma_f32_16x16x32_bf16 v[42:45], v[168:171], v[184:187], v[42:45]
	v_mfma_f32_16x16x32_bf16 v[28:31], v[158:161], v[192:195], v[28:31]
	v_mfma_f32_16x16x32_bf16 v[24:27], v[168:171], v[192:195], v[24:27]
	v_mfma_f32_16x16x32_bf16 v[12:15], v[158:161], v[216:219], v[12:15]
	v_mfma_f32_16x16x32_bf16 v[8:11], v[168:171], v[216:219], v[8:11]
	s_setprio 0
	s_barrier
	s_add_i32 s8, s70, 0x40000
	s_add_u32 s8, s21, s8
	s_addc_u32 s9, s22, 0
	s_add_i32 s71, s73, s23
	v_lshl_add_u64 v[144:145], s[8:9], 0, v[32:33]
	s_mov_b32 m0, s71
	s_nop 0
	global_load_lds_dwordx4 v[144:145], off
	v_lshl_add_u64 v[144:145], s[8:9], 0, v[130:131]
	s_add_i32 m0, s71, 0x2000
	s_nop 0
	global_load_lds_dwordx4 v[144:145], off
	s_waitcnt vmcnt(6)
	s_barrier
	s_setprio 1
	v_mfma_f32_16x16x32_bf16 v[54:57], v[220:223], v[172:175], v[54:57]
	v_mfma_f32_16x16x32_bf16 v[50:53], v[228:231], v[172:175], v[50:53]
	v_mfma_f32_16x16x32_bf16 v[38:41], v[220:223], v[180:183], v[38:41]
	v_mfma_f32_16x16x32_bf16 v[34:37], v[228:231], v[180:183], v[34:37]
	v_mfma_f32_16x16x32_bf16 v[20:23], v[220:223], v[188:191], v[20:23]
	v_mfma_f32_16x16x32_bf16 v[16:19], v[228:231], v[188:191], v[16:19]
	v_mfma_f32_16x16x32_bf16 v[4:7], v[220:223], v[196:199], v[4:7]
	v_mfma_f32_16x16x32_bf16 v[0:3], v[228:231], v[196:199], v[0:3]
	v_mfma_f32_16x16x32_bf16 v[54:57], v[224:227], v[176:179], v[54:57]
	v_mfma_f32_16x16x32_bf16 v[50:53], v[232:235], v[176:179], v[50:53]
	v_mfma_f32_16x16x32_bf16 v[38:41], v[224:227], v[184:187], v[38:41]
	v_mfma_f32_16x16x32_bf16 v[34:37], v[232:235], v[184:187], v[34:37]
	v_mfma_f32_16x16x32_bf16 v[20:23], v[224:227], v[192:195], v[20:23]
	v_mfma_f32_16x16x32_bf16 v[16:19], v[232:235], v[192:195], v[16:19]
	v_mfma_f32_16x16x32_bf16 v[4:7], v[224:227], v[216:219], v[4:7]
	v_mfma_f32_16x16x32_bf16 v[0:3], v[232:235], v[216:219], v[0:3]
	s_setprio 0
	s_add_i32 s71, 0, 0x18000
	v_add_u32_e32 v167, s71, v150
	s_barrier
	ds_read_b128 v[144:147], v167
	ds_read_b128 v[158:161], v167 offset:1024
	ds_read_b128 v[162:165], v167 offset:2048
	ds_read_b128 v[168:171], v167 offset:3072
	s_add_i32 s72, s72, 0x40000
	s_add_u32 s8, s14, s72
	s_addc_u32 s9, s15, 0
	s_mov_b32 m0, s26
	v_lshl_add_u64 v[208:209], s[8:9], 0, v[134:135]
	ds_read_b128 v[172:175], v151 offset:32768
	ds_read_b128 v[176:179], v151 offset:33792
	ds_read_b128 v[180:183], v151 offset:34816
	ds_read_b128 v[184:187], v151 offset:35840
	ds_read_b128 v[188:191], v151 offset:36864
	ds_read_b128 v[192:195], v151 offset:37888
	ds_read_b128 v[196:199], v151 offset:38912
	ds_read_b128 v[216:219], v151 offset:39936
	global_load_lds_dwordx4 v[208:209], off
	v_lshl_add_u64 v[208:209], s[8:9], 0, v[132:133]
	s_mov_b32 m0, s27
	s_nop 0
	global_load_lds_dwordx4 v[208:209], off
	s_waitcnt lgkmcnt(8)
	s_barrier
; #define PG8_STAGE(bufoff, gbase, goff, voff) do { _Pragma("unroll") for (int _i = 0; _i < 2; ++_i) \
;     __builtin_amdgcn_global_load_lds((const unsigned*)((gbase) + (size_t)(goff) + (voff)[_i]), (LAS unsigned*)(lds + (bufoff) + ldsw + _i * 8192), 16, 0, 0); } while (0)
; #define PG8_LDA(dst, b, h) do { _Pragma("unroll") for (int m = 0; m < 4; ++m) _Pragma("unroll") for (int k = 0; k < 2; ++k) dst[m][k] = *(const LAS bf16x8*)(lds + PG8_SA(b, h) + aoff + m * 2048 + k * 1024); } while (0)
; #define PG8_LDB(dst, b, h) do { _Pragma("unroll") for (int n = 0; n < 2; ++n) _Pragma("unroll") for (int k = 0; k < 2; ++k) dst[n][k] = *(const LAS bf16x8*)(lds + PG8_SB(b, h) + boff + n * 2048 + k * 1024); } while (0)
; #define PG8_MMA(ai, bj, At, Bt) do { __builtin_amdgcn_s_setprio(1); _Pragma("unroll") for (int m = 0; m < 4; ++m) _Pragma("unroll") for (int n = 0; n < 2; ++n) _Pragma("unroll") for (int k = 0; k < 2; ++k) \
;     acc[ai][bj][m][n] = __builtin_amdgcn_mfma_f32_16x16x32_bf16(Bt[n][k], At[m][k], acc[ai][bj][m][n], 0, 0, 0); __builtin_amdgcn_s_setprio(0); } while (0)
; #define PG8_WAIT_L(n) asm volatile("s_waitcnt lgkmcnt(" #n ")" ::: "memory")
; #define PG8_BAR __builtin_amdgcn_s_barrier()
; #define PG8_SCHED __builtin_amdgcn_sched_barrier(0)
; template <class Epi>
; DI void gemm_phase(LAS unsigned char* lds, const GemmD g, const Order& S, const Epi& E) {
;     ...
;       PG8_WAIT_L(8); PG8_BAR; PG8_WAIT_L(0); PG8_MMA(0, 0, At, B0); PG8_BAR; PG8_SCHED;
;       PG8_LDB(B1, 1, 1); PG8_STAGE(PG8_SB(1, 0), gB, b3, voffB);
;       PG8_BAR; PG8_WAIT_L(0); PG8_MMA(0, 1, At, B1); PG8_BAR;
;       PG8_LDA(At, 1, 1); PG8_STAGE(PG8_SA(1, 0), gA, a3, voffA);
;       PG8_BAR; PG8_WAIT_L(0); PG8_MMA(1, 0, At, B0); PG8_BAR; PG8_SCHED;
;       PG8_STAGE(PG8_SB(1, 1), gB, b3 + hstepB, voffB);
	s_waitcnt lgkmcnt(0)
	s_setprio 1
	s_waitcnt lgkmcnt(0)
	v_mfma_f32_16x16x32_bf16 v[126:129], v[144:147], v[172:175], v[126:129]
	v_mfma_f32_16x16x32_bf16 v[122:125], v[162:165], v[172:175], v[122:125]
	v_mfma_f32_16x16x32_bf16 v[110:113], v[144:147], v[180:183], v[110:113]
	v_mfma_f32_16x16x32_bf16 v[106:109], v[162:165], v[180:183], v[106:109]
	v_mfma_f32_16x16x32_bf16 v[94:97], v[144:147], v[188:191], v[94:97]
	v_mfma_f32_16x16x32_bf16 v[90:93], v[162:165], v[188:191], v[90:93]
	v_mfma_f32_16x16x32_bf16 v[78:81], v[144:147], v[196:199], v[78:81]
	v_mfma_f32_16x16x32_bf16 v[74:77], v[162:165], v[196:199], v[74:77]
	v_mfma_f32_16x16x32_bf16 v[126:129], v[158:161], v[176:179], v[126:129]
	v_mfma_f32_16x16x32_bf16 v[122:125], v[168:171], v[176:179], v[122:125]
	v_mfma_f32_16x16x32_bf16 v[110:113], v[158:161], v[184:187], v[110:113]
	v_mfma_f32_16x16x32_bf16 v[106:109], v[168:171], v[184:187], v[106:109]
	v_mfma_f32_16x16x32_bf16 v[94:97], v[158:161], v[192:195], v[94:97]
	v_mfma_f32_16x16x32_bf16 v[90:93], v[168:171], v[192:195], v[90:93]
	v_mfma_f32_16x16x32_bf16 v[78:81], v[158:161], v[216:219], v[78:81]
	v_mfma_f32_16x16x32_bf16 v[74:77], v[168:171], v[216:219], v[74:77]
	s_setprio 0
	s_barrier
	s_add_i32 s72, 0, 0x1c000
	s_add_i32 s8, s71, s23
	v_add_u32_e32 v167, s72, v150
	v_lshl_add_u64 v[148:149], v[148:149], 0, s[50:51]
	s_mov_b32 m0, s8
	ds_read_b128 v[220:223], v167
	ds_read_b128 v[224:227], v167 offset:1024
	ds_read_b128 v[228:231], v167 offset:2048
	ds_read_b128 v[232:235], v167 offset:3072
	global_load_lds_dwordx4 v[148:149], off
	v_lshl_add_u64 v[148:149], v[152:153], 0, s[50:51]
	s_add_i32 m0, s8, 0x2000
	s_nop 0
	global_load_lds_dwordx4 v[148:149], off
	s_barrier
	s_waitcnt lgkmcnt(0)
	s_setprio 1
	s_waitcnt lgkmcnt(0)
	v_mfma_f32_16x16x32_bf16 v[118:121], v[220:223], v[172:175], v[118:121]
	v_mfma_f32_16x16x32_bf16 v[114:117], v[228:231], v[172:175], v[114:117]
	v_mfma_f32_16x16x32_bf16 v[102:105], v[220:223], v[180:183], v[102:105]
	v_mfma_f32_16x16x32_bf16 v[98:101], v[228:231], v[180:183], v[98:101]
	v_mfma_f32_16x16x32_bf16 v[86:89], v[220:223], v[188:191], v[86:89]
	v_mfma_f32_16x16x32_bf16 v[82:85], v[228:231], v[188:191], v[82:85]
	v_mfma_f32_16x16x32_bf16 v[70:73], v[220:223], v[196:199], v[70:73]
	v_mfma_f32_16x16x32_bf16 v[66:69], v[228:231], v[196:199], v[66:69]
	v_mfma_f32_16x16x32_bf16 v[118:121], v[224:227], v[176:179], v[118:121]
	v_mfma_f32_16x16x32_bf16 v[114:117], v[232:235], v[176:179], v[114:117]
	v_mfma_f32_16x16x32_bf16 v[102:105], v[224:227], v[184:187], v[102:105]
	v_mfma_f32_16x16x32_bf16 v[98:101], v[232:235], v[184:187], v[98:101]
	v_mfma_f32_16x16x32_bf16 v[86:89], v[224:227], v[192:195], v[86:89]
	v_mfma_f32_16x16x32_bf16 v[82:85], v[232:235], v[192:195], v[82:85]
	v_mfma_f32_16x16x32_bf16 v[70:73], v[224:227], v[216:219], v[70:73]
	v_mfma_f32_16x16x32_bf16 v[66:69], v[232:235], v[216:219], v[66:69]
	s_setprio 0
	s_mov_b32 m0, s28
	v_lshl_add_u64 v[148:149], v[200:201], 0, s[50:51]
	s_barrier
	ds_read_b128 v[172:175], v151 offset:49152
	ds_read_b128 v[176:179], v151 offset:50176
	ds_read_b128 v[180:183], v151 offset:51200
	ds_read_b128 v[184:187], v151 offset:52224
	ds_read_b128 v[188:191], v151 offset:53248
	ds_read_b128 v[192:195], v151 offset:54272
	ds_read_b128 v[196:199], v151 offset:55296
	ds_read_b128 v[216:219], v151 offset:56320
	global_load_lds_dwordx4 v[148:149], off
	v_lshl_add_u64 v[148:149], v[204:205], 0, s[50:51]
	s_mov_b32 m0, s29
	s_nop 0
	global_load_lds_dwordx4 v[148:149], off
	s_barrier
	s_waitcnt lgkmcnt(0)
	s_setprio 1
	s_waitcnt lgkmcnt(0)
	v_mfma_f32_16x16x32_bf16 v[62:65], v[144:147], v[172:175], v[62:65]
	v_mfma_f32_16x16x32_bf16 v[58:61], v[162:165], v[172:175], v[58:61]
	v_mfma_f32_16x16x32_bf16 v[46:49], v[144:147], v[180:183], v[46:49]
	v_mfma_f32_16x16x32_bf16 v[42:45], v[162:165], v[180:183], v[42:45]
	v_mfma_f32_16x16x32_bf16 v[28:31], v[144:147], v[188:191], v[28:31]
	v_mfma_f32_16x16x32_bf16 v[24:27], v[162:165], v[188:191], v[24:27]
	v_mfma_f32_16x16x32_bf16 v[12:15], v[144:147], v[196:199], v[12:15]
	v_mfma_f32_16x16x32_bf16 v[8:11], v[162:165], v[196:199], v[8:11]
	v_mfma_f32_16x16x32_bf16 v[62:65], v[158:161], v[176:179], v[62:65]
	v_mfma_f32_16x16x32_bf16 v[58:61], v[168:171], v[176:179], v[58:61]
	v_mfma_f32_16x16x32_bf16 v[46:49], v[158:161], v[184:187], v[46:49]
	v_mfma_f32_16x16x32_bf16 v[42:45], v[168:171], v[184:187], v[42:45]
	v_mfma_f32_16x16x32_bf16 v[28:31], v[158:161], v[192:195], v[28:31]
	v_mfma_f32_16x16x32_bf16 v[24:27], v[168:171], v[192:195], v[24:27]
	v_mfma_f32_16x16x32_bf16 v[12:15], v[158:161], v[216:219], v[12:15]
	v_mfma_f32_16x16x32_bf16 v[8:11], v[168:171], v[216:219], v[8:11]
	s_setprio 0
	s_barrier
	s_add_i32 s70, s70, 0x40080
	s_add_u32 s8, s21, s70
	s_addc_u32 s9, s22, 0
	s_add_i32 s70, s72, s23
	v_lshl_add_u64 v[144:145], s[8:9], 0, v[32:33]
	s_mov_b32 m0, s70
	s_nop 0
	global_load_lds_dwordx4 v[144:145], off
	v_lshl_add_u64 v[144:145], s[8:9], 0, v[130:131]
	s_add_i32 m0, s70, 0x2000
	s_nop 0
	global_load_lds_dwordx4 v[144:145], off
	s_waitcnt vmcnt(6)
	s_barrier
; DI int get_tid() { int t = __builtin_amdgcn_workitem_id_x(); asm volatile("" : "+v"(t)); return t; }
; DI unsigned pk2(float a, float b) { f2_t v = {a, b}; bf2_t r = __builtin_convertvector(v, bf2_t); return __builtin_bit_cast(unsigned, r); }
; #define PG8_MMA(ai, bj, At, Bt) do { __builtin_amdgcn_s_setprio(1); _Pragma("unroll") for (int m = 0; m < 4; ++m) _Pragma("unroll") for (int n = 0; n < 2; ++n) _Pragma("unroll") for (int k = 0; k < 2; ++k) \
;     acc[ai][bj][m][n] = __builtin_amdgcn_mfma_f32_16x16x32_bf16(Bt[n][k], At[m][k], acc[ai][bj][m][n], 0, 0, 0); __builtin_amdgcn_s_setprio(0); } while (0)
; #define PG8_WAIT_V(n) asm volatile("s_waitcnt vmcnt(" #n ")" ::: "memory")
; #define PG8_BAR __builtin_amdgcn_s_barrier()
; template <class Epi>
; DI void gemm_phase(LAS unsigned char* lds, const GemmD g, const Order& S, const Epi& E) {
;     ...
;       PG8_WAIT_V(6); PG8_BAR; PG8_MMA(1, 1, At, B1); PG8_BAR;
;     }
;     const bool keep = E(acc, cur, wr, wc, fr, fq);
;   DI bool operator()(f32x4 (&acc)[2][2][4][2], const Unit& u, int, int, int, int) const {
;     const int tid_ = get_tid(), wr = tid_ >> 8, wc = (tid_ >> 6) & 3, fr = tid_ & 15, fq = (tid_ >> 4) & 3;
;     const int row0 = u.pm * BM + wr * 64 + fr, col0 = u.pn * BM + wc * 32 + 8 * fq;
; #pragma unroll
;     for (int ai = 0; ai < 2; ++ai)
; #pragma unroll
;       for (int m = 0; m < 4; ++m) {
;         const int r = row0 + ai * HALF + m * 16;
;         u16* rowp = act + (size_t)r * 4096 + col0;
;         const float rstd = __builtin_amdgcn_rsqf(rowss[r] * (1.f / 1024.f) + 1e-6f);
;         const float* bp = bias + (size_t)((u.pm * BM) / S_) * 4096 + col0;
; #pragma unroll
;         for (int bj = 0; bj < 2; ++bj) {
;           f32x4 v0 = acc[ai][bj][m][0] * rstd + *(const f32x4*)(bp + bj * HALF);
;           f32x4 v1 = acc[ai][bj][m][1] * rstd + *(const f32x4*)(bp + bj * HALF + 4);
; #pragma unroll
;           for (int j = 0; j < 4; ++j) { v0[j] = fmaxf(v0[j], 0.f); v0[j] *= v0[j]; v1[j] = fmaxf(v1[j], 0.f); v1[j] *= v1[j]; }
;           u32x4 w;
;           w.x = pk2(v0[0], v0[1]); w.y = pk2(v0[2], v0[3]); w.z = pk2(v1[0], v1[1]); w.w = pk2(v1[2], v1[3]);
;           *(u32x4*)(rowp + bj * HALF) = w;
	s_setprio 1
	v_mfma_f32_16x16x32_bf16 v[54:57], v[220:223], v[172:175], v[54:57]
	v_mfma_f32_16x16x32_bf16 v[50:53], v[228:231], v[172:175], v[50:53]
	v_mfma_f32_16x16x32_bf16 v[38:41], v[220:223], v[180:183], v[38:41]
	v_mfma_f32_16x16x32_bf16 v[34:37], v[228:231], v[180:183], v[34:37]
	v_mfma_f32_16x16x32_bf16 v[20:23], v[220:223], v[188:191], v[20:23]
	v_mfma_f32_16x16x32_bf16 v[16:19], v[228:231], v[188:191], v[16:19]
	v_mfma_f32_16x16x32_bf16 v[4:7], v[220:223], v[196:199], v[4:7]
	v_mfma_f32_16x16x32_bf16 v[0:3], v[228:231], v[196:199], v[0:3]
	v_mfma_f32_16x16x32_bf16 v[54:57], v[224:227], v[176:179], v[54:57]
	v_mfma_f32_16x16x32_bf16 v[50:53], v[232:235], v[176:179], v[50:53]
	v_mfma_f32_16x16x32_bf16 v[38:41], v[224:227], v[184:187], v[38:41]
	v_mfma_f32_16x16x32_bf16 v[34:37], v[232:235], v[184:187], v[34:37]
	v_mfma_f32_16x16x32_bf16 v[20:23], v[224:227], v[192:195], v[20:23]
	v_mfma_f32_16x16x32_bf16 v[16:19], v[232:235], v[192:195], v[16:19]
	v_mfma_f32_16x16x32_bf16 v[4:7], v[224:227], v[216:219], v[4:7]
	v_mfma_f32_16x16x32_bf16 v[0:3], v[232:235], v[216:219], v[0:3]
	s_setprio 0
	s_add_i32 s69, s69, 2
	s_add_u32 s6, s6, 0x100
	s_addc_u32 s7, s7, 0
	s_cmp_gt_u32 s69, 13
	s_barrier
	s_cbranch_scc0 .LBB0_235
	s_nop 0
	v_mov_b32_e32 v141, v202
	s_lshl_b32 s6, s39, 8
	v_ashrrev_i32_e32 v140, 2, v141
	v_and_b32_e32 v142, 0xffffffc0, v140
	v_lshrrev_b32_e32 v140, 1, v141
	v_and_or_b32 v141, v141, 15, s6
	s_ashr_i32 s6, s39, 31
	v_add_u32_e32 v146, v141, v142
	s_lshr_b32 s6, s6, 26
	s_add_i32 s6, s39, s6
	v_ashrrev_i32_e32 v147, 31, v146
	s_ashr_i32 s6, s6, 6
	v_lshl_add_u64 v[144:145], v[146:147], 2, s[16:17]
	s_ashr_i32 s7, s6, 31
	global_load_dword v168, v[144:145], off
	global_load_dword v170, v[144:145], off offset:64
	global_load_dword v172, v[144:145], off offset:128
	global_load_dword v174, v[144:145], off offset:192
	global_load_dword v184, v[144:145], off offset:512
	global_load_dword v186, v[144:145], off offset:576
	global_load_dword v188, v[144:145], off offset:640
	global_load_dword v190, v[144:145], off offset:704
	v_and_b32_e32 v140, 0x78, v140
	s_lshl_b64 s[6:7], s[6:7], 14
	v_lshl_or_b32 v140, s65, 8, v140
	s_add_u32 s6, s18, s6
	v_ashrrev_i32_e32 v141, 31, v140
	s_addc_u32 s7, s19, s7
	v_lshl_add_u64 v[142:143], v[140:141], 2, s[6:7]
	global_load_dwordx4 v[158:161], v[142:143], off
	global_load_dwordx4 v[162:165], v[142:143], off offset:16
	global_load_dwordx4 v[176:179], v[142:143], off offset:512
	global_load_dwordx4 v[180:183], v[142:143], off offset:528
	v_lshlrev_b64 v[152:153], 13, v[146:147]
	s_mov_b32 s68, s38
	s_mov_b32 s48, s31
	s_mov_b32 s39, s11
	s_mov_b32 s65, s10
	v_lshlrev_b64 v[148:149], 1, v[140:141]
	v_lshl_add_u64 v[140:141], s[12:13], 0, v[152:153]
	v_lshl_add_u64 v[140:141], v[140:141], 0, v[148:149]
	s_and_b64 vcc, exec, s[4:5]
	s_waitcnt vmcnt(0)
	v_fmamk_f32 v168, v168, 0x3a800000, v203
	v_fmamk_f32 v170, v170, 0x3a800000, v203
	v_fmamk_f32 v172, v172, 0x3a800000, v203
	v_fmamk_f32 v174, v174, 0x3a800000, v203
	v_fmamk_f32 v184, v184, 0x3a800000, v203
	v_fmamk_f32 v186, v186, 0x3a800000, v203
	v_fmamk_f32 v188, v188, 0x3a800000, v203
	v_fmamk_f32 v190, v190, 0x3a800000, v203
	v_rsq_f32_e32 v168, v168
	v_rsq_f32_e32 v170, v170
	v_rsq_f32_e32 v172, v172
	v_rsq_f32_e32 v174, v174
	v_rsq_f32_e32 v184, v184
	v_rsq_f32_e32 v186, v186
	v_rsq_f32_e32 v188, v188
	v_rsq_f32_e32 v190, v190
	v_pk_fma_f32 v[128:129], v[128:129], v[168:169], v[160:161] op_sel_hi:[1,0,1]
	v_pk_fma_f32 v[126:127], v[126:127], v[168:169], v[158:159] op_sel_hi:[1,0,1]
	v_pk_fma_f32 v[124:125], v[124:125], v[168:169], v[164:165] op_sel_hi:[1,0,1]
	v_pk_fma_f32 v[122:123], v[122:123], v[168:169], v[162:163] op_sel_hi:[1,0,1]
	v_max_f32_e32 v126, 0, v126
	v_max_f32_e32 v122, 0, v122
	v_max_f32_e32 v127, 0, v127
	v_max_f32_e32 v123, 0, v123
	v_max_f32_e32 v128, 0, v128
	v_max_f32_e32 v124, 0, v124
	v_max_f32_e32 v129, 0, v129
	v_max_f32_e32 v125, 0, v125
	v_pk_mul_f32 v[126:127], v[126:127], v[126:127]
	v_pk_mul_f32 v[122:123], v[122:123], v[122:123]
	v_pk_mul_f32 v[128:129], v[128:129], v[128:129]
	v_pk_mul_f32 v[124:125], v[124:125], v[124:125]
	v_cvt_pk_bf16_f32 v126, v126, v127
	v_cvt_pk_bf16_f32 v127, v128, v129
	v_cvt_pk_bf16_f32 v128, v122, v123
	v_cvt_pk_bf16_f32 v129, v124, v125
	global_store_dwordx4 v[140:141], v[126:129], off
	v_pk_fma_f32 v[120:121], v[120:121], v[168:169], v[178:179] op_sel_hi:[1,0,1]
	v_pk_fma_f32 v[118:119], v[118:119], v[168:169], v[176:177] op_sel_hi:[1,0,1]
	v_pk_fma_f32 v[116:117], v[116:117], v[168:169], v[182:183] op_sel_hi:[1,0,1]
	v_pk_fma_f32 v[114:115], v[114:115], v[168:169], v[180:181] op_sel_hi:[1,0,1]
	v_max_f32_e32 v118, 0, v118
	v_max_f32_e32 v114, 0, v114
	v_max_f32_e32 v119, 0, v119
	v_max_f32_e32 v115, 0, v115
	v_max_f32_e32 v120, 0, v120
	v_max_f32_e32 v116, 0, v116
	v_max_f32_e32 v121, 0, v121
	v_max_f32_e32 v117, 0, v117
	v_pk_mul_f32 v[118:119], v[118:119], v[118:119]
	v_pk_mul_f32 v[114:115], v[114:115], v[114:115]
	v_pk_mul_f32 v[120:121], v[120:121], v[120:121]
	v_pk_mul_f32 v[116:117], v[116:117], v[116:117]
	v_cvt_pk_bf16_f32 v118, v118, v119
	v_cvt_pk_bf16_f32 v119, v120, v121
	v_cvt_pk_bf16_f32 v120, v114, v115
	v_cvt_pk_bf16_f32 v121, v116, v117
	global_store_dwordx4 v[140:141], v[118:121], off offset:256
	s_mov_b64 s[6:7], 0x20000
	v_lshl_add_u64 v[192:193], v[140:141], 0, s[6:7]
	v_pk_fma_f32 v[112:113], v[112:113], v[170:171], v[160:161] op_sel_hi:[1,0,1]
	v_pk_fma_f32 v[110:111], v[110:111], v[170:171], v[158:159] op_sel_hi:[1,0,1]
	v_pk_fma_f32 v[108:109], v[108:109], v[170:171], v[164:165] op_sel_hi:[1,0,1]
	v_pk_fma_f32 v[106:107], v[106:107], v[170:171], v[162:163] op_sel_hi:[1,0,1]
; DI unsigned pk2(float a, float b) { f2_t v = {a, b}; bf2_t r = __builtin_convertvector(v, bf2_t); return __builtin_bit_cast(unsigned, r); }
;   DI bool operator()(f32x4 (&acc)[2][2][4][2], const Unit& u, int, int, int, int) const {
;     ...
;       for (int m = 0; m < 4; ++m) {
;         const int r = row0 + ai * HALF + m * 16;
;         u16* rowp = act + (size_t)r * 4096 + col0;
;         const float rstd = __builtin_amdgcn_rsqf(rowss[r] * (1.f / 1024.f) + 1e-6f);
;         const float* bp = bias + (size_t)((u.pm * BM) / S_) * 4096 + col0;
; #pragma unroll
;         for (int bj = 0; bj < 2; ++bj) {
;           f32x4 v0 = acc[ai][bj][m][0] * rstd + *(const f32x4*)(bp + bj * HALF);
;           f32x4 v1 = acc[ai][bj][m][1] * rstd + *(const f32x4*)(bp + bj * HALF + 4);
; #pragma unroll
;           for (int j = 0; j < 4; ++j) { v0[j] = fmaxf(v0[j], 0.f); v0[j] *= v0[j]; v1[j] = fmaxf(v1[j], 0.f); v1[j] *= v1[j]; }
;           u32x4 w;
;           w.x = pk2(v0[0], v0[1]); w.y = pk2(v0[2], v0[3]); w.z = pk2(v1[0], v1[1]); w.w = pk2(v1[2], v1[3]);
;           *(u32x4*)(rowp + bj * HALF) = w;
	v_max_f32_e32 v110, 0, v110
	v_max_f32_e32 v106, 0, v106
	v_max_f32_e32 v111, 0, v111
	v_max_f32_e32 v107, 0, v107
	v_max_f32_e32 v112, 0, v112
	v_max_f32_e32 v108, 0, v108
	v_max_f32_e32 v113, 0, v113
	v_max_f32_e32 v109, 0, v109
	v_pk_mul_f32 v[110:111], v[110:111], v[110:111]
	v_pk_mul_f32 v[106:107], v[106:107], v[106:107]
	v_pk_mul_f32 v[112:113], v[112:113], v[112:113]
	v_pk_mul_f32 v[108:109], v[108:109], v[108:109]
	v_cvt_pk_bf16_f32 v110, v110, v111
	v_cvt_pk_bf16_f32 v111, v112, v113
	v_cvt_pk_bf16_f32 v112, v106, v107
	v_cvt_pk_bf16_f32 v113, v108, v109
	global_store_dwordx4 v[192:193], v[110:113], off
	v_pk_fma_f32 v[104:105], v[104:105], v[170:171], v[178:179] op_sel_hi:[1,0,1]
	v_pk_fma_f32 v[102:103], v[102:103], v[170:171], v[176:177] op_sel_hi:[1,0,1]
	v_pk_fma_f32 v[100:101], v[100:101], v[170:171], v[182:183] op_sel_hi:[1,0,1]
	v_pk_fma_f32 v[98:99], v[98:99], v[170:171], v[180:181] op_sel_hi:[1,0,1]
	v_max_f32_e32 v102, 0, v102
	v_max_f32_e32 v98, 0, v98
	v_max_f32_e32 v103, 0, v103
	v_max_f32_e32 v99, 0, v99
	v_max_f32_e32 v104, 0, v104
	v_max_f32_e32 v100, 0, v100
	v_max_f32_e32 v105, 0, v105
	v_max_f32_e32 v101, 0, v101
	v_pk_mul_f32 v[102:103], v[102:103], v[102:103]
	v_pk_mul_f32 v[98:99], v[98:99], v[98:99]
	v_pk_mul_f32 v[104:105], v[104:105], v[104:105]
	v_pk_mul_f32 v[100:101], v[100:101], v[100:101]
	v_cvt_pk_bf16_f32 v102, v102, v103
	v_cvt_pk_bf16_f32 v103, v104, v105
	v_cvt_pk_bf16_f32 v104, v98, v99
	v_cvt_pk_bf16_f32 v105, v100, v101
	global_store_dwordx4 v[192:193], v[102:105], off offset:256
	s_mov_b64 s[6:7], 0x40000
	v_lshl_add_u64 v[192:193], v[140:141], 0, s[6:7]
	v_pk_fma_f32 v[96:97], v[96:97], v[172:173], v[160:161] op_sel_hi:[1,0,1]
	v_pk_fma_f32 v[94:95], v[94:95], v[172:173], v[158:159] op_sel_hi:[1,0,1]
	v_pk_fma_f32 v[92:93], v[92:93], v[172:173], v[164:165] op_sel_hi:[1,0,1]
	v_pk_fma_f32 v[90:91], v[90:91], v[172:173], v[162:163] op_sel_hi:[1,0,1]
	v_max_f32_e32 v94, 0, v94
	v_max_f32_e32 v90, 0, v90
	v_max_f32_e32 v95, 0, v95
	v_max_f32_e32 v91, 0, v91
	v_max_f32_e32 v96, 0, v96
	v_max_f32_e32 v92, 0, v92
	v_max_f32_e32 v97, 0, v97
	v_max_f32_e32 v93, 0, v93
	v_pk_mul_f32 v[94:95], v[94:95], v[94:95]
	v_pk_mul_f32 v[90:91], v[90:91], v[90:91]
	v_pk_mul_f32 v[96:97], v[96:97], v[96:97]
	v_pk_mul_f32 v[92:93], v[92:93], v[92:93]
	v_cvt_pk_bf16_f32 v94, v94, v95
	v_cvt_pk_bf16_f32 v95, v96, v97
	v_cvt_pk_bf16_f32 v96, v90, v91
	v_cvt_pk_bf16_f32 v97, v92, v93
	global_store_dwordx4 v[192:193], v[94:97], off
	v_pk_fma_f32 v[88:89], v[88:89], v[172:173], v[178:179] op_sel_hi:[1,0,1]
	v_pk_fma_f32 v[86:87], v[86:87], v[172:173], v[176:177] op_sel_hi:[1,0,1]
	v_pk_fma_f32 v[84:85], v[84:85], v[172:173], v[182:183] op_sel_hi:[1,0,1]
	v_pk_fma_f32 v[82:83], v[82:83], v[172:173], v[180:181] op_sel_hi:[1,0,1]
	v_max_f32_e32 v86, 0, v86
	v_max_f32_e32 v82, 0, v82
	v_max_f32_e32 v87, 0, v87
	v_max_f32_e32 v83, 0, v83
	v_max_f32_e32 v88, 0, v88
	v_max_f32_e32 v84, 0, v84
	v_max_f32_e32 v89, 0, v89
	v_max_f32_e32 v85, 0, v85
	v_pk_mul_f32 v[86:87], v[86:87], v[86:87]
	v_pk_mul_f32 v[82:83], v[82:83], v[82:83]
	v_pk_mul_f32 v[88:89], v[88:89], v[88:89]
	v_pk_mul_f32 v[84:85], v[84:85], v[84:85]
	v_cvt_pk_bf16_f32 v86, v86, v87
	v_cvt_pk_bf16_f32 v87, v88, v89
	v_cvt_pk_bf16_f32 v88, v82, v83
	v_cvt_pk_bf16_f32 v89, v84, v85
	global_store_dwordx4 v[192:193], v[86:89], off offset:256
	s_mov_b64 s[6:7], 0x60000
	v_lshl_add_u64 v[192:193], v[140:141], 0, s[6:7]
	v_pk_fma_f32 v[80:81], v[80:81], v[174:175], v[160:161] op_sel_hi:[1,0,1]
	v_pk_fma_f32 v[78:79], v[78:79], v[174:175], v[158:159] op_sel_hi:[1,0,1]
	v_pk_fma_f32 v[76:77], v[76:77], v[174:175], v[164:165] op_sel_hi:[1,0,1]
	v_pk_fma_f32 v[74:75], v[74:75], v[174:175], v[162:163] op_sel_hi:[1,0,1]
	v_max_f32_e32 v78, 0, v78
	v_max_f32_e32 v74, 0, v74
	v_max_f32_e32 v79, 0, v79
	v_max_f32_e32 v75, 0, v75
	v_max_f32_e32 v80, 0, v80
	v_max_f32_e32 v76, 0, v76
	v_max_f32_e32 v81, 0, v81
	v_max_f32_e32 v77, 0, v77
	v_pk_mul_f32 v[78:79], v[78:79], v[78:79]
	v_pk_mul_f32 v[74:75], v[74:75], v[74:75]
	v_pk_mul_f32 v[80:81], v[80:81], v[80:81]
	v_pk_mul_f32 v[76:77], v[76:77], v[76:77]
	v_cvt_pk_bf16_f32 v78, v78, v79
	v_cvt_pk_bf16_f32 v79, v80, v81
	v_cvt_pk_bf16_f32 v80, v74, v75
	v_cvt_pk_bf16_f32 v81, v76, v77
	global_store_dwordx4 v[192:193], v[78:81], off
	v_pk_fma_f32 v[72:73], v[72:73], v[174:175], v[178:179] op_sel_hi:[1,0,1]
	v_pk_fma_f32 v[70:71], v[70:71], v[174:175], v[176:177] op_sel_hi:[1,0,1]
	v_pk_fma_f32 v[68:69], v[68:69], v[174:175], v[182:183] op_sel_hi:[1,0,1]
	v_pk_fma_f32 v[66:67], v[66:67], v[174:175], v[180:181] op_sel_hi:[1,0,1]
	v_max_f32_e32 v70, 0, v70
	v_max_f32_e32 v66, 0, v66
	v_max_f32_e32 v71, 0, v71
	v_max_f32_e32 v67, 0, v67
	v_max_f32_e32 v72, 0, v72
	v_max_f32_e32 v68, 0, v68
	v_max_f32_e32 v73, 0, v73
	v_max_f32_e32 v69, 0, v69
	v_pk_mul_f32 v[70:71], v[70:71], v[70:71]
	v_pk_mul_f32 v[66:67], v[66:67], v[66:67]
	v_pk_mul_f32 v[72:73], v[72:73], v[72:73]
	v_pk_mul_f32 v[68:69], v[68:69], v[68:69]
	v_cvt_pk_bf16_f32 v70, v70, v71
	v_cvt_pk_bf16_f32 v71, v72, v73
	v_cvt_pk_bf16_f32 v72, v66, v67
	v_cvt_pk_bf16_f32 v73, v68, v69
	global_store_dwordx4 v[192:193], v[70:73], off offset:256
	s_mov_b64 s[6:7], 0x100000
	v_lshl_add_u64 v[192:193], v[140:141], 0, s[6:7]
	v_pk_fma_f32 v[64:65], v[64:65], v[184:185], v[160:161] op_sel_hi:[1,0,1]
	v_pk_fma_f32 v[62:63], v[62:63], v[184:185], v[158:159] op_sel_hi:[1,0,1]
	v_pk_fma_f32 v[60:61], v[60:61], v[184:185], v[164:165] op_sel_hi:[1,0,1]
	v_pk_fma_f32 v[58:59], v[58:59], v[184:185], v[162:163] op_sel_hi:[1,0,1]
	v_max_f32_e32 v62, 0, v62
	v_max_f32_e32 v58, 0, v58
; DI unsigned pk2(float a, float b) { f2_t v = {a, b}; bf2_t r = __builtin_convertvector(v, bf2_t); return __builtin_bit_cast(unsigned, r); }
; template <class Epi>
; DI void gemm_phase(LAS unsigned char* lds, const GemmD g, const Order& S, const Epi& E) {
;     ...
;     const bool keep = E(acc, cur, wr, wc, fr, fq);
;     if (!has_next) break;
;   DI bool operator()(f32x4 (&acc)[2][2][4][2], const Unit& u, int, int, int, int) const {
;     ...
;       for (int m = 0; m < 4; ++m) {
;         const int r = row0 + ai * HALF + m * 16;
;         u16* rowp = act + (size_t)r * 4096 + col0;
;         const float rstd = __builtin_amdgcn_rsqf(rowss[r] * (1.f / 1024.f) + 1e-6f);
;         const float* bp = bias + (size_t)((u.pm * BM) / S_) * 4096 + col0;
; #pragma unroll
;         for (int bj = 0; bj < 2; ++bj) {
;           f32x4 v0 = acc[ai][bj][m][0] * rstd + *(const f32x4*)(bp + bj * HALF);
;           f32x4 v1 = acc[ai][bj][m][1] * rstd + *(const f32x4*)(bp + bj * HALF + 4);
; #pragma unroll
;           for (int j = 0; j < 4; ++j) { v0[j] = fmaxf(v0[j], 0.f); v0[j] *= v0[j]; v1[j] = fmaxf(v1[j], 0.f); v1[j] *= v1[j]; }
;           u32x4 w;
;           w.x = pk2(v0[0], v0[1]); w.y = pk2(v0[2], v0[3]); w.z = pk2(v1[0], v1[1]); w.w = pk2(v1[2], v1[3]);
;           *(u32x4*)(rowp + bj * HALF) = w;
	v_max_f32_e32 v63, 0, v63
	v_max_f32_e32 v59, 0, v59
	v_max_f32_e32 v64, 0, v64
	v_max_f32_e32 v60, 0, v60
	v_max_f32_e32 v65, 0, v65
	v_max_f32_e32 v61, 0, v61
	v_pk_mul_f32 v[62:63], v[62:63], v[62:63]
	v_pk_mul_f32 v[58:59], v[58:59], v[58:59]
	v_pk_mul_f32 v[64:65], v[64:65], v[64:65]
	v_pk_mul_f32 v[60:61], v[60:61], v[60:61]
	v_cvt_pk_bf16_f32 v62, v62, v63
	v_cvt_pk_bf16_f32 v63, v64, v65
	v_cvt_pk_bf16_f32 v64, v58, v59
	v_cvt_pk_bf16_f32 v65, v60, v61
	global_store_dwordx4 v[192:193], v[62:65], off
	v_pk_fma_f32 v[56:57], v[56:57], v[184:185], v[178:179] op_sel_hi:[1,0,1]
	v_pk_fma_f32 v[54:55], v[54:55], v[184:185], v[176:177] op_sel_hi:[1,0,1]
	v_pk_fma_f32 v[52:53], v[52:53], v[184:185], v[182:183] op_sel_hi:[1,0,1]
	v_pk_fma_f32 v[50:51], v[50:51], v[184:185], v[180:181] op_sel_hi:[1,0,1]
	v_max_f32_e32 v54, 0, v54
	v_max_f32_e32 v50, 0, v50
	v_max_f32_e32 v55, 0, v55
	v_max_f32_e32 v51, 0, v51
	v_max_f32_e32 v56, 0, v56
	v_max_f32_e32 v52, 0, v52
	v_max_f32_e32 v57, 0, v57
	v_max_f32_e32 v53, 0, v53
	v_pk_mul_f32 v[54:55], v[54:55], v[54:55]
	v_pk_mul_f32 v[50:51], v[50:51], v[50:51]
	v_pk_mul_f32 v[56:57], v[56:57], v[56:57]
	v_pk_mul_f32 v[52:53], v[52:53], v[52:53]
	v_cvt_pk_bf16_f32 v54, v54, v55
	v_cvt_pk_bf16_f32 v55, v56, v57
	v_cvt_pk_bf16_f32 v56, v50, v51
	v_cvt_pk_bf16_f32 v57, v52, v53
	global_store_dwordx4 v[192:193], v[54:57], off offset:256
	s_mov_b64 s[6:7], 0x120000
	v_lshl_add_u64 v[192:193], v[140:141], 0, s[6:7]
	v_pk_fma_f32 v[48:49], v[48:49], v[186:187], v[160:161] op_sel_hi:[1,0,1]
	v_pk_fma_f32 v[46:47], v[46:47], v[186:187], v[158:159] op_sel_hi:[1,0,1]
	v_pk_fma_f32 v[44:45], v[44:45], v[186:187], v[164:165] op_sel_hi:[1,0,1]
	v_pk_fma_f32 v[42:43], v[42:43], v[186:187], v[162:163] op_sel_hi:[1,0,1]
	v_max_f32_e32 v46, 0, v46
	v_max_f32_e32 v42, 0, v42
	v_max_f32_e32 v47, 0, v47
	v_max_f32_e32 v43, 0, v43
	v_max_f32_e32 v48, 0, v48
	v_max_f32_e32 v44, 0, v44
	v_max_f32_e32 v49, 0, v49
	v_max_f32_e32 v45, 0, v45
	v_pk_mul_f32 v[46:47], v[46:47], v[46:47]
	v_pk_mul_f32 v[42:43], v[42:43], v[42:43]
	v_pk_mul_f32 v[48:49], v[48:49], v[48:49]
	v_pk_mul_f32 v[44:45], v[44:45], v[44:45]
	v_cvt_pk_bf16_f32 v46, v46, v47
	v_cvt_pk_bf16_f32 v47, v48, v49
	v_cvt_pk_bf16_f32 v48, v42, v43
	v_cvt_pk_bf16_f32 v49, v44, v45
	global_store_dwordx4 v[192:193], v[46:49], off
	v_pk_fma_f32 v[40:41], v[40:41], v[186:187], v[178:179] op_sel_hi:[1,0,1]
	v_pk_fma_f32 v[38:39], v[38:39], v[186:187], v[176:177] op_sel_hi:[1,0,1]
	v_pk_fma_f32 v[36:37], v[36:37], v[186:187], v[182:183] op_sel_hi:[1,0,1]
	v_pk_fma_f32 v[34:35], v[34:35], v[186:187], v[180:181] op_sel_hi:[1,0,1]
	v_max_f32_e32 v38, 0, v38
	v_max_f32_e32 v34, 0, v34
	v_max_f32_e32 v39, 0, v39
	v_max_f32_e32 v35, 0, v35
	v_max_f32_e32 v40, 0, v40
	v_max_f32_e32 v36, 0, v36
	v_max_f32_e32 v41, 0, v41
	v_max_f32_e32 v37, 0, v37
	v_pk_mul_f32 v[38:39], v[38:39], v[38:39]
	v_pk_mul_f32 v[34:35], v[34:35], v[34:35]
	v_pk_mul_f32 v[40:41], v[40:41], v[40:41]
	v_pk_mul_f32 v[36:37], v[36:37], v[36:37]
	v_cvt_pk_bf16_f32 v38, v38, v39
	v_cvt_pk_bf16_f32 v39, v40, v41
	v_cvt_pk_bf16_f32 v40, v34, v35
	v_cvt_pk_bf16_f32 v41, v36, v37
	global_store_dwordx4 v[192:193], v[38:41], off offset:256
	s_mov_b64 s[6:7], 0x140000
	v_lshl_add_u64 v[192:193], v[140:141], 0, s[6:7]
	v_pk_fma_f32 v[30:31], v[30:31], v[188:189], v[160:161] op_sel_hi:[1,0,1]
	v_pk_fma_f32 v[28:29], v[28:29], v[188:189], v[158:159] op_sel_hi:[1,0,1]
	v_pk_fma_f32 v[26:27], v[26:27], v[188:189], v[164:165] op_sel_hi:[1,0,1]
	v_pk_fma_f32 v[24:25], v[24:25], v[188:189], v[162:163] op_sel_hi:[1,0,1]
	v_max_f32_e32 v28, 0, v28
	v_max_f32_e32 v24, 0, v24
	v_max_f32_e32 v29, 0, v29
	v_max_f32_e32 v25, 0, v25
	v_max_f32_e32 v30, 0, v30
	v_max_f32_e32 v26, 0, v26
	v_max_f32_e32 v31, 0, v31
	v_max_f32_e32 v27, 0, v27
	v_pk_mul_f32 v[28:29], v[28:29], v[28:29]
	v_pk_mul_f32 v[24:25], v[24:25], v[24:25]
	v_pk_mul_f32 v[30:31], v[30:31], v[30:31]
	v_pk_mul_f32 v[26:27], v[26:27], v[26:27]
	v_cvt_pk_bf16_f32 v28, v28, v29
	v_cvt_pk_bf16_f32 v29, v30, v31
	v_cvt_pk_bf16_f32 v30, v24, v25
	v_cvt_pk_bf16_f32 v31, v26, v27
	global_store_dwordx4 v[192:193], v[28:31], off
	v_pk_fma_f32 v[22:23], v[22:23], v[188:189], v[178:179] op_sel_hi:[1,0,1]
	v_pk_fma_f32 v[20:21], v[20:21], v[188:189], v[176:177] op_sel_hi:[1,0,1]
	v_pk_fma_f32 v[18:19], v[18:19], v[188:189], v[182:183] op_sel_hi:[1,0,1]
	v_pk_fma_f32 v[16:17], v[16:17], v[188:189], v[180:181] op_sel_hi:[1,0,1]
	v_max_f32_e32 v20, 0, v20
	v_max_f32_e32 v16, 0, v16
	v_max_f32_e32 v21, 0, v21
	v_max_f32_e32 v17, 0, v17
	v_max_f32_e32 v22, 0, v22
	v_max_f32_e32 v18, 0, v18
	v_max_f32_e32 v23, 0, v23
	v_max_f32_e32 v19, 0, v19
	v_pk_mul_f32 v[20:21], v[20:21], v[20:21]
	v_pk_mul_f32 v[16:17], v[16:17], v[16:17]
	v_pk_mul_f32 v[22:23], v[22:23], v[22:23]
	v_pk_mul_f32 v[18:19], v[18:19], v[18:19]
	v_cvt_pk_bf16_f32 v20, v20, v21
	v_cvt_pk_bf16_f32 v21, v22, v23
	v_cvt_pk_bf16_f32 v22, v16, v17
	v_cvt_pk_bf16_f32 v23, v18, v19
	global_store_dwordx4 v[192:193], v[20:23], off offset:256
	s_mov_b64 s[6:7], 0x160000
	v_lshl_add_u64 v[192:193], v[140:141], 0, s[6:7]
	v_pk_fma_f32 v[14:15], v[14:15], v[190:191], v[160:161] op_sel_hi:[1,0,1]
	v_pk_fma_f32 v[12:13], v[12:13], v[190:191], v[158:159] op_sel_hi:[1,0,1]
	v_pk_fma_f32 v[10:11], v[10:11], v[190:191], v[164:165] op_sel_hi:[1,0,1]
	v_pk_fma_f32 v[8:9], v[8:9], v[190:191], v[162:163] op_sel_hi:[1,0,1]
	v_max_f32_e32 v12, 0, v12
	v_max_f32_e32 v8, 0, v8
	v_max_f32_e32 v13, 0, v13
	v_max_f32_e32 v9, 0, v9
	v_max_f32_e32 v14, 0, v14
	v_max_f32_e32 v10, 0, v10
	v_max_f32_e32 v15, 0, v15
	v_max_f32_e32 v11, 0, v11
	v_pk_mul_f32 v[12:13], v[12:13], v[12:13]
	v_pk_mul_f32 v[8:9], v[8:9], v[8:9]
	v_pk_mul_f32 v[14:15], v[14:15], v[14:15]
	v_pk_mul_f32 v[10:11], v[10:11], v[10:11]
	v_cvt_pk_bf16_f32 v12, v12, v13
	v_cvt_pk_bf16_f32 v13, v14, v15
	v_cvt_pk_bf16_f32 v14, v8, v9
	v_cvt_pk_bf16_f32 v15, v10, v11
	global_store_dwordx4 v[192:193], v[12:15], off
	v_pk_fma_f32 v[6:7], v[6:7], v[190:191], v[178:179] op_sel_hi:[1,0,1]
	v_pk_fma_f32 v[4:5], v[4:5], v[190:191], v[176:177] op_sel_hi:[1,0,1]
	v_pk_fma_f32 v[2:3], v[2:3], v[190:191], v[182:183] op_sel_hi:[1,0,1]
	v_pk_fma_f32 v[0:1], v[0:1], v[190:191], v[180:181] op_sel_hi:[1,0,1]
	v_max_f32_e32 v4, 0, v4
	v_max_f32_e32 v0, 0, v0
	v_max_f32_e32 v5, 0, v5
	v_max_f32_e32 v1, 0, v1
	v_max_f32_e32 v6, 0, v6
	v_max_f32_e32 v2, 0, v2
	v_max_f32_e32 v7, 0, v7
	v_max_f32_e32 v3, 0, v3
	v_pk_mul_f32 v[4:5], v[4:5], v[4:5]
	v_pk_mul_f32 v[0:1], v[0:1], v[0:1]
	v_pk_mul_f32 v[6:7], v[6:7], v[6:7]
	v_pk_mul_f32 v[2:3], v[2:3], v[2:3]
	v_cvt_pk_bf16_f32 v4, v4, v5
	v_cvt_pk_bf16_f32 v5, v6, v7
	v_cvt_pk_bf16_f32 v6, v0, v1
	v_cvt_pk_bf16_f32 v7, v2, v3
	global_store_dwordx4 v[192:193], v[4:7], off offset:256
	s_cbranch_vccz .LBB0_228
	s_waitcnt vmcnt(0)
	s_cmpk_gt_u32 s20, 0xff
	s_cbranch_scc1 .LBB0_239
	s_barrier
